# RS4+prio with V4 softmax (running-max test replaced by a row-sum check after the exponentials; baseline max/rescale rule applied in the rare path on recomputed scores)
# speedup vs baseline: 1.0254x; 1.0058x over previous
; __device__ __forceinline__ int v_rd_base(int lane) { return ((lane & 3) << 3) | (((lane >> 2) & 3) << 6) | (((lane >> 4) & 1) << 5) | (((lane >> 5) & 1) << 8); }
; __device__ __forceinline__ int v_rd_base(int lane) { return ((lane & 3) << 3) | (((lane >> 2) & 3) << 6) | (((lane >> 4) & 1) << 5) | (((lane >> 5) & 1) << 8); }
; __device__ __forceinline__ void attn_unit256q(const bf16* __restrict__ Qb, const unsigned char* __restrict__ Kc, const unsigned char* __restrict__ Kl, const float* __restrict__ Sc, const float* __restrict__ Sl, ...
;     ...
;   const int kx = (r32 & 7) << 4;
;   const lds_cptr kp0 = shm3 + LDS_K + r32 * 128, vp0 = shm3 + LDS_V + v_rd_base(lane);
;   float ksn0 = Sc[0], ksn1 = Sc[1];
;   constexpr float BIAS = 12582912.f;
;   i32x16 bini;
; #pragma unroll
;   for (int r = 0; r < 16; ++r) bini[r] = 0x4B400000;
;   asm volatile("" : "+v"(bini));
;   float m_reg = -1e30f, l_reg = 0.f, alpha = 1.f; f32x16 o[8];
; #pragma unroll
;   for (int d = 0; d < 8; ++d) o[d] = f32x16{};
;   f32x16 p; i32x16 p8; bf16x8 pa0, pa1; float ks0, ks1;
.LBB0_527:
	s_or_b64 exec, exec, s[0:1]
	s_add_u32 s22, s30, 0x1ca00000
	v_readlane_b32 s0, v243, 50
	s_addc_u32 s23, s31, 0
	s_ashr_i32 s24, s33, 31
	s_ashr_i32 s25, s0, 31
	s_mov_b32 s5, 0
	v_mov_b64_e32 v[198:199], 0x87f
	v_mov_b32_e32 v201, 0
	s_mov_b32 s26, 0x41000000
	s_mov_b32 s27, 0x42fe0000
	s_mov_b32 s34, 0x40c0c00
	s_mov_b64 s[6:7], 0x80
	s_mov_b64 s[8:9], 0x100
	s_mov_b64 s[10:11], 0x180
	v_mov_b64_e32 v[202:203], 0x7ff
	v_mov_b32_e32 v217, 0x7ffff3
	s_waitcnt lgkmcnt(0)
	v_mov_b32_e32 v2, 0x4b400000
	s_mov_b32 s100, 0x4b400000
	s_mov_b32 s101, 0x453a4000
	s_mov_b32 s35, 0
	s_barrier
	s_branch .LBB0_530

.LBB0_538:
	s_add_i32 s2, s79, -1
	s_min_u32 s85, s2, s84
	s_lshl_b32 s4, s85, 6
	s_cmp_lt_u32 s85, 4
	s_cselect_b64 s[2:3], -1, 0
	s_add_i32 s88, s4, 0xffffff00
	s_and_b64 s[86:87], s[2:3], exec
	s_cselect_b32 s4, s4, s88
	s_cselect_b32 s88, s17, s73
	s_cselect_b32 s89, s16, s72
	s_lshl_b64 s[86:87], s[4:5], 7
	s_add_u32 s86, s89, s86
	s_addc_u32 s87, s88, s87
	s_lshl_b32 s88, s85, 1
	s_mov_b32 s89, s5
	s_lshl_b64 s[88:89], s[88:89], 2
	s_add_u32 s85, s18, s88
	s_addc_u32 s90, s19, s89
	s_add_u32 s88, s74, s88
	s_addc_u32 s89, s75, s89
	s_add_u32 s88, s88, 0xffffffe0
	s_addc_u32 s89, s89, -1
	s_and_b64 s[2:3], s[2:3], exec
	s_cselect_b32 s3, s90, s89
	s_cselect_b32 s2, s85, s88
	s_waitcnt vmcnt(0) lgkmcnt(0)
	s_barrier
	s_setprio 1
	s_waitcnt vmcnt(0)
	global_load_dwordx2 v[208:209], v201, s[2:3]
	s_cselect_b32 s85, s21, s77
	s_cselect_b32 s88, s20, s76
	s_lshl_b64 s[2:3], s[4:5], 9
	s_add_u32 s2, s88, s2
	ds_read_b128 v[180:183], v225
	ds_read_b128 v[184:187], v226
	s_addc_u32 s3, s85, s3
	s_cmp_lg_u32 0, -1
	s_cselect_b32 s4, 0, 0
	s_add_i32 s85, s4, s80
	s_add_i32 s4, s4, s81
	s_addk_i32 s85, 0x4000
	s_add_i32 s88, s4, 0x10000
	s_waitcnt lgkmcnt(1)
	v_mfma_i32_32x32x32_i8 v[148:163], v[180:183], v[164:167], v[132:147]
	ds_read_b128 v[180:183], v227
	s_waitcnt lgkmcnt(1)
	v_mfma_i32_32x32x32_i8 v[148:163], v[184:187], v[168:171], v[148:163]
	ds_read_b128 v[188:191], v228
	s_waitcnt lgkmcnt(1)
	v_mfma_i32_32x32x32_i8 v[148:163], v[180:183], v[172:175], v[148:163]
	ds_read_b64_tr_b16 v[184:185], v3 offset:32768
	ds_read_b64_tr_b16 v[186:187], v3 offset:36864
	s_waitcnt lgkmcnt(2)
	v_mfma_i32_32x32x32_i8 v[148:163], v[188:191], v[176:179], v[148:163]
	ds_read_b64_tr_b16 v[180:181], v3 offset:33280
	ds_read_b64_tr_b16 v[182:183], v3 offset:37376
	s_nop 9
	v_mul_f32_e32 v189, v221, v206
	v_fma_f32 v190, s100, v189, v255
	v_fma_f32 v148, v148, v189, -v190
	v_fma_f32 v149, v149, v189, -v190
	v_exp_f32_e32 v148, v148
	v_fma_f32 v150, v150, v189, -v190
	v_exp_f32_e32 v149, v149
	v_fma_f32 v151, v151, v189, -v190
	v_exp_f32_e32 v150, v150
	v_fma_f32 v152, v152, v189, -v190
	v_exp_f32_e32 v151, v151
	v_fma_f32 v153, v153, v189, -v190
	v_exp_f32_e32 v152, v152
	v_fma_f32 v154, v154, v189, -v190
	v_exp_f32_e32 v153, v153
	v_fma_f32 v155, v155, v189, -v190
	v_exp_f32_e32 v154, v154
	v_fma_f32 v156, v156, v189, -v190
	v_exp_f32_e32 v155, v155
	v_fma_f32 v157, v157, v189, -v190
	v_exp_f32_e32 v156, v156
	v_fma_f32 v158, v158, v189, -v190
	v_exp_f32_e32 v157, v157
	v_fma_f32 v159, v159, v189, -v190
	v_exp_f32_e32 v158, v158
	v_fma_f32 v160, v160, v189, -v190
	v_exp_f32_e32 v159, v159
	v_fma_f32 v161, v161, v189, -v190
	v_exp_f32_e32 v160, v160
	v_fma_f32 v162, v162, v189, -v190
	v_exp_f32_e32 v161, v161
	v_fma_f32 v163, v163, v189, -v190
	v_exp_f32_e32 v162, v162
	v_exp_f32_e32 v163, v163
	v_add_f32_e32 v188, v148, v149
	v_add_f32_e32 v189, v150, v151
	v_add_f32_e32 v190, v152, v153
	v_add_f32_e32 v191, v154, v155
	v_add_f32_e32 v192, v156, v157
	v_add_f32_e32 v193, v158, v159
	v_add_f32_e32 v194, v160, v161
	v_add_f32_e32 v195, v162, v163
	v_add_f32_e32 v188, v188, v189
	v_add_f32_e32 v190, v190, v191
	v_add_f32_e32 v192, v192, v193
	v_add_f32_e32 v194, v194, v195
	v_add_f32_e32 v188, v188, v190
	v_add_f32_e32 v192, v192, v194
	v_add_f32_e32 v188, v188, v192
	v_cmp_lt_f32_e32 vcc, s101, v188
	s_cbranch_vccnz .Lv4_rare_h1
.Lv4_cont_h1:
	v_add_f32_e32 v224, v224, v188
	v_cvt_pk_bf16_f32 v155, v154, v155
	v_cvt_pk_bf16_f32 v154, v152, v153
	v_cvt_pk_bf16_f32 v152, v148, v149
	v_cvt_pk_bf16_f32 v153, v150, v151
	v_cvt_pk_bf16_f32 v148, v156, v157
	v_cvt_pk_bf16_f32 v149, v158, v159
	v_cvt_pk_bf16_f32 v150, v160, v161
	v_cvt_pk_bf16_f32 v151, v162, v163
	s_barrier
	s_setprio 0
	s_waitcnt lgkmcnt(2)
	v_mfma_f32_32x32x16_bf16 v[4:19], v[152:155], v[184:187], v[4:19]
	ds_read_b64_tr_b16 v[156:157], v3 offset:33792
	ds_read_b64_tr_b16 v[158:159], v3 offset:37888
	s_waitcnt lgkmcnt(2)
	v_mfma_f32_32x32x16_bf16 v[116:131], v[152:155], v[180:183], v[116:131]
	ds_read_b64_tr_b16 v[160:161], v3 offset:34304
	ds_read_b64_tr_b16 v[162:163], v3 offset:38400
	s_add_i32 m0, s80, 0x4000
	s_nop 0
	global_load_lds_dwordx4 v200, s[86:87]
	s_waitcnt lgkmcnt(2)
	v_mfma_f32_32x32x16_bf16 v[100:115], v[152:155], v[156:159], v[100:115]
	ds_read_b64_tr_b16 v[156:157], v3 offset:34816
	ds_read_b64_tr_b16 v[158:159], v3 offset:38912
	s_waitcnt lgkmcnt(2)
	v_mfma_f32_32x32x16_bf16 v[84:99], v[152:155], v[160:163], v[84:99]
	ds_read_b64_tr_b16 v[160:161], v3 offset:35328
	ds_read_b64_tr_b16 v[162:163], v3 offset:39424
	s_add_i32 m0, s81, 0x10000
	s_nop 0
	global_load_lds_dwordx4 v204, s[2:3]
	s_waitcnt lgkmcnt(2)
	v_mfma_f32_32x32x16_bf16 v[68:83], v[152:155], v[156:159], v[68:83]
	ds_read_b64_tr_b16 v[156:157], v3 offset:35840
	ds_read_b64_tr_b16 v[158:159], v3 offset:39936
	s_waitcnt lgkmcnt(2)
	v_mfma_f32_32x32x16_bf16 v[52:67], v[152:155], v[160:163], v[52:67]
	ds_read_b64_tr_b16 v[160:161], v3 offset:36352
	ds_read_b64_tr_b16 v[162:163], v3 offset:40448
	s_add_u32 s2, s2, 0x80
	s_addc_u32 s3, s3, 0
	s_add_i32 m0, s81, 0x10400
	s_nop 0
	global_load_lds_dwordx4 v204, s[2:3]
	s_waitcnt lgkmcnt(2)
	v_mfma_f32_32x32x16_bf16 v[36:51], v[152:155], v[156:159], v[36:51]
	ds_read_b64_tr_b16 v[156:157], v3 offset:40960
	ds_read_b64_tr_b16 v[158:159], v3 offset:45056
	s_waitcnt lgkmcnt(2)
	v_mfma_f32_32x32x16_bf16 v[20:35], v[152:155], v[160:163], v[20:35]
	ds_read_b64_tr_b16 v[152:153], v3 offset:41472
	ds_read_b64_tr_b16 v[154:155], v3 offset:45568
	s_add_u32 s2, s2, 0x80
	s_addc_u32 s3, s3, 0
	s_add_i32 m0, s81, 0x10800
	s_nop 0
	global_load_lds_dwordx4 v204, s[2:3]
	s_waitcnt lgkmcnt(2)
	v_mfma_f32_32x32x16_bf16 v[4:19], v[148:151], v[156:159], v[4:19]
	ds_read_b64_tr_b16 v[156:157], v3 offset:41984
	ds_read_b64_tr_b16 v[158:159], v3 offset:46080
	s_waitcnt lgkmcnt(2)
	v_mfma_f32_32x32x16_bf16 v[116:131], v[148:151], v[152:155], v[116:131]
	ds_read_b64_tr_b16 v[152:153], v3 offset:42496
	ds_read_b64_tr_b16 v[154:155], v3 offset:46592
	s_add_u32 s2, s2, 0x80
	s_addc_u32 s3, s3, 0
	s_add_i32 m0, s81, 0x10c00
	s_nop 0
	global_load_lds_dwordx4 v204, s[2:3]
	s_waitcnt lgkmcnt(2)
	v_mfma_f32_32x32x16_bf16 v[100:115], v[148:151], v[156:159], v[100:115]
	ds_read_b64_tr_b16 v[156:157], v3 offset:43008
	ds_read_b64_tr_b16 v[158:159], v3 offset:47104
	s_waitcnt lgkmcnt(2)
	v_mfma_f32_32x32x16_bf16 v[84:99], v[148:151], v[152:155], v[84:99]
	ds_read_b64_tr_b16 v[152:153], v3 offset:43520
	ds_read_b64_tr_b16 v[154:155], v3 offset:47616
	s_waitcnt lgkmcnt(2)
	v_mfma_f32_32x32x16_bf16 v[68:83], v[148:151], v[156:159], v[68:83]
	ds_read_b64_tr_b16 v[156:157], v3 offset:44032
	ds_read_b64_tr_b16 v[158:159], v3 offset:48128
	s_waitcnt lgkmcnt(2)
	v_mfma_f32_32x32x16_bf16 v[52:67], v[148:151], v[152:155], v[52:67]
	ds_read_b64_tr_b16 v[152:153], v3 offset:44544
	ds_read_b64_tr_b16 v[154:155], v3 offset:48640
	s_waitcnt lgkmcnt(2)
	v_mfma_f32_32x32x16_bf16 v[36:51], v[148:151], v[156:159], v[36:51]
	s_waitcnt lgkmcnt(0)
	v_mfma_f32_32x32x16_bf16 v[20:35], v[148:151], v[152:155], v[20:35]
	s_barrier
	s_setprio 1
	ds_read_b128 v[180:183], v225 offset:4096
	ds_read_b128 v[184:187], v226 offset:4096
	s_waitcnt lgkmcnt(1)
	v_mfma_i32_32x32x32_i8 v[148:163], v[180:183], v[164:167], v[132:147]
	ds_read_b128 v[180:183], v227 offset:4096
	s_waitcnt lgkmcnt(1)
	v_mfma_i32_32x32x32_i8 v[148:163], v[184:187], v[168:171], v[148:163]
	ds_read_b128 v[188:191], v228 offset:4096
	s_waitcnt lgkmcnt(1)
	v_mfma_i32_32x32x32_i8 v[148:163], v[180:183], v[172:175], v[148:163]
	ds_read_b64_tr_b16 v[184:185], v3 offset:49152
	ds_read_b64_tr_b16 v[186:187], v3 offset:53248
	s_waitcnt lgkmcnt(2)
	v_mfma_i32_32x32x32_i8 v[148:163], v[188:191], v[176:179], v[148:163]
	ds_read_b64_tr_b16 v[180:181], v3 offset:49664
	ds_read_b64_tr_b16 v[182:183], v3 offset:53760
	s_nop 9
	v_mul_f32_e32 v189, v221, v207
	v_fma_f32 v190, s100, v189, v255
	v_fma_f32 v148, v148, v189, -v190
	v_fma_f32 v149, v149, v189, -v190
	v_exp_f32_e32 v148, v148
	v_fma_f32 v150, v150, v189, -v190
	v_exp_f32_e32 v149, v149
	v_fma_f32 v151, v151, v189, -v190
	v_exp_f32_e32 v150, v150
	v_fma_f32 v152, v152, v189, -v190
	v_exp_f32_e32 v151, v151
	v_fma_f32 v153, v153, v189, -v190
	v_exp_f32_e32 v152, v152
	v_fma_f32 v154, v154, v189, -v190
	v_exp_f32_e32 v153, v153
	v_fma_f32 v155, v155, v189, -v190
	v_exp_f32_e32 v154, v154
	v_fma_f32 v156, v156, v189, -v190
	v_exp_f32_e32 v155, v155
	v_fma_f32 v157, v157, v189, -v190
	v_exp_f32_e32 v156, v156
	v_fma_f32 v158, v158, v189, -v190
	v_exp_f32_e32 v157, v157
	v_fma_f32 v159, v159, v189, -v190
	v_exp_f32_e32 v158, v158
	v_fma_f32 v160, v160, v189, -v190
	v_exp_f32_e32 v159, v159
	v_fma_f32 v161, v161, v189, -v190
	v_exp_f32_e32 v160, v160
	v_fma_f32 v162, v162, v189, -v190
	v_exp_f32_e32 v161, v161
	v_fma_f32 v163, v163, v189, -v190
	v_exp_f32_e32 v162, v162
	v_exp_f32_e32 v163, v163
	v_add_f32_e32 v188, v148, v149
	v_add_f32_e32 v189, v150, v151
	v_add_f32_e32 v190, v152, v153
	v_add_f32_e32 v191, v154, v155
	v_add_f32_e32 v192, v156, v157
	v_add_f32_e32 v193, v158, v159
	v_add_f32_e32 v194, v160, v161
	v_add_f32_e32 v195, v162, v163
	v_add_f32_e32 v188, v188, v189
	v_add_f32_e32 v190, v190, v191
	v_add_f32_e32 v192, v192, v193
	v_add_f32_e32 v194, v194, v195
	v_add_f32_e32 v188, v188, v190
	v_add_f32_e32 v192, v192, v194
	v_add_f32_e32 v188, v188, v192
	v_cmp_lt_f32_e32 vcc, s101, v188
	s_cbranch_vccnz .Lv4_rare_h2
.Lv4_cont_h2:
	v_add_f32_e32 v224, v224, v188
	v_cvt_pk_bf16_f32 v155, v154, v155
	v_cvt_pk_bf16_f32 v154, v152, v153
	v_cvt_pk_bf16_f32 v152, v148, v149
	v_cvt_pk_bf16_f32 v153, v150, v151
	v_cvt_pk_bf16_f32 v148, v156, v157
	v_cvt_pk_bf16_f32 v149, v158, v159
	v_cvt_pk_bf16_f32 v150, v160, v161
	v_cvt_pk_bf16_f32 v151, v162, v163
	s_barrier
	s_setprio 0
	s_waitcnt lgkmcnt(2)
	v_mfma_f32_32x32x16_bf16 v[4:19], v[152:155], v[184:187], v[4:19]
	ds_read_b64_tr_b16 v[156:157], v3 offset:50176
	ds_read_b64_tr_b16 v[158:159], v3 offset:54272
	s_waitcnt lgkmcnt(2)
	v_mfma_f32_32x32x16_bf16 v[116:131], v[152:155], v[180:183], v[116:131]
	ds_read_b64_tr_b16 v[160:161], v3 offset:50688
	ds_read_b64_tr_b16 v[162:163], v3 offset:54784
	s_waitcnt lgkmcnt(2)
	v_mfma_f32_32x32x16_bf16 v[100:115], v[152:155], v[156:159], v[100:115]
	ds_read_b64_tr_b16 v[156:157], v3 offset:51200
	ds_read_b64_tr_b16 v[158:159], v3 offset:55296
	s_waitcnt lgkmcnt(2)
	v_mfma_f32_32x32x16_bf16 v[84:99], v[152:155], v[160:163], v[84:99]
	ds_read_b64_tr_b16 v[160:161], v3 offset:51712
	ds_read_b64_tr_b16 v[162:163], v3 offset:55808
	s_waitcnt lgkmcnt(2)
	v_mfma_f32_32x32x16_bf16 v[68:83], v[152:155], v[156:159], v[68:83]
	ds_read_b64_tr_b16 v[156:157], v3 offset:52224
	ds_read_b64_tr_b16 v[158:159], v3 offset:56320
	s_waitcnt lgkmcnt(2)
	v_mfma_f32_32x32x16_bf16 v[52:67], v[152:155], v[160:163], v[52:67]
	ds_read_b64_tr_b16 v[160:161], v3 offset:52736
	ds_read_b64_tr_b16 v[162:163], v3 offset:56832
	s_waitcnt lgkmcnt(2)
	v_mfma_f32_32x32x16_bf16 v[36:51], v[152:155], v[156:159], v[36:51]
	ds_read_b64_tr_b16 v[156:157], v3 offset:57344
	ds_read_b64_tr_b16 v[158:159], v3 offset:61440
	s_waitcnt lgkmcnt(2)
	v_mfma_f32_32x32x16_bf16 v[20:35], v[152:155], v[160:163], v[20:35]
	ds_read_b64_tr_b16 v[152:153], v3 offset:57856
	ds_read_b64_tr_b16 v[154:155], v3 offset:61952
	s_waitcnt lgkmcnt(2)
	v_mfma_f32_32x32x16_bf16 v[4:19], v[148:151], v[156:159], v[4:19]
	ds_read_b64_tr_b16 v[156:157], v3 offset:58368
	ds_read_b64_tr_b16 v[158:159], v3 offset:62464
	s_waitcnt lgkmcnt(2)
	v_mfma_f32_32x32x16_bf16 v[116:131], v[148:151], v[152:155], v[116:131]
	ds_read_b64_tr_b16 v[152:153], v3 offset:58880
	ds_read_b64_tr_b16 v[154:155], v3 offset:62976
	s_waitcnt lgkmcnt(2)
	v_mfma_f32_32x32x16_bf16 v[100:115], v[148:151], v[156:159], v[100:115]
	ds_read_b64_tr_b16 v[156:157], v3 offset:59392
	ds_read_b64_tr_b16 v[158:159], v3 offset:63488
	s_waitcnt lgkmcnt(2)
	v_mfma_f32_32x32x16_bf16 v[84:99], v[148:151], v[152:155], v[84:99]
	ds_read_b64_tr_b16 v[152:153], v3 offset:59904
	ds_read_b64_tr_b16 v[154:155], v3 offset:64000
	s_waitcnt lgkmcnt(2)
	v_mfma_f32_32x32x16_bf16 v[68:83], v[148:151], v[156:159], v[68:83]
	ds_read_b64_tr_b16 v[156:157], v3 offset:60416
	ds_read_b64_tr_b16 v[158:159], v3 offset:64512
	s_waitcnt lgkmcnt(2)
	v_mfma_f32_32x32x16_bf16 v[52:67], v[148:151], v[152:155], v[52:67]
	ds_read_b64_tr_b16 v[152:153], v3 offset:60928
	ds_read_b64_tr_b16 v[154:155], v3 offset:65024
	s_waitcnt lgkmcnt(2)
	v_mfma_f32_32x32x16_bf16 v[36:51], v[148:151], v[156:159], v[36:51]
	s_waitcnt lgkmcnt(0)
	v_mfma_f32_32x32x16_bf16 v[20:35], v[148:151], v[152:155], v[20:35]
	s_min_u32 s85, s79, s84
	s_lshl_b32 s4, s85, 6
	s_cmp_lt_u32 s85, 4
	s_cselect_b64 s[2:3], -1, 0
	s_add_i32 s88, s4, 0xffffff00
	s_and_b64 s[86:87], s[2:3], exec
	s_cselect_b32 s4, s4, s88
	s_cselect_b32 s88, s17, s73
	s_cselect_b32 s89, s16, s72
	s_lshl_b64 s[86:87], s[4:5], 7
	s_add_u32 s86, s89, s86
	s_addc_u32 s87, s88, s87
	s_lshl_b32 s88, s85, 1
	s_mov_b32 s89, s5
	s_lshl_b64 s[88:89], s[88:89], 2
	s_add_u32 s85, s18, s88
	s_addc_u32 s90, s19, s89
	s_add_u32 s88, s74, s88
	s_addc_u32 s89, s75, s89
	s_add_u32 s88, s88, 0xffffffe0
	s_addc_u32 s89, s89, -1
	s_and_b64 s[2:3], s[2:3], exec
	s_waitcnt vmcnt(0)
	v_mov_b32_e32 v236, v209
	s_cselect_b32 s3, s90, s89
	s_cselect_b32 s2, s85, s88
	s_waitcnt vmcnt(0) lgkmcnt(0)
	s_barrier
	s_setprio 1
	global_load_dwordx2 v[206:207], v201, s[2:3]
	ds_read_b128 v[180:183], v225 offset:16384
	ds_read_b128 v[184:187], v226 offset:16384
	s_cselect_b32 s85, s21, s77
	s_cselect_b32 s88, s20, s76
	s_lshl_b64 s[2:3], s[4:5], 9
	s_add_u32 s2, s88, s2
	s_addc_u32 s3, s85, s3
	s_waitcnt lgkmcnt(1)
	v_mfma_i32_32x32x32_i8 v[148:163], v[180:183], v[164:167], v[132:147]
	ds_read_b128 v[180:183], v227 offset:16384
	s_waitcnt lgkmcnt(1)
	v_mfma_i32_32x32x32_i8 v[148:163], v[184:187], v[168:171], v[148:163]
	ds_read_b128 v[188:191], v228 offset:16384
	s_waitcnt lgkmcnt(1)
	v_mfma_i32_32x32x32_i8 v[148:163], v[180:183], v[172:175], v[148:163]
	ds_read_b64_tr_b16 v[184:185], v222 offset:32768
	ds_read_b64_tr_b16 v[186:187], v222 offset:36864
	s_waitcnt lgkmcnt(2)
	v_mfma_i32_32x32x32_i8 v[148:163], v[188:191], v[176:179], v[148:163]
	ds_read_b64_tr_b16 v[180:181], v222 offset:33280
	ds_read_b64_tr_b16 v[182:183], v222 offset:37376
	s_nop 9
	s_mov_b32 s90, s94
	v_mul_f32_e32 v189, v221, v208
	v_fma_f32 v190, s100, v189, v255
	v_fma_f32 v148, v148, v189, -v190
	v_fma_f32 v149, v149, v189, -v190
	v_exp_f32_e32 v148, v148
	v_fma_f32 v150, v150, v189, -v190
	v_exp_f32_e32 v149, v149
	v_fma_f32 v151, v151, v189, -v190
	v_exp_f32_e32 v150, v150
	v_fma_f32 v152, v152, v189, -v190
	v_exp_f32_e32 v151, v151
	v_fma_f32 v153, v153, v189, -v190
	v_exp_f32_e32 v152, v152
	v_fma_f32 v154, v154, v189, -v190
	v_exp_f32_e32 v153, v153
	v_fma_f32 v155, v155, v189, -v190
	v_exp_f32_e32 v154, v154
	v_fma_f32 v156, v156, v189, -v190
	v_exp_f32_e32 v155, v155
	v_fma_f32 v157, v157, v189, -v190
	v_exp_f32_e32 v156, v156
	v_fma_f32 v158, v158, v189, -v190
	v_exp_f32_e32 v157, v157
	v_fma_f32 v159, v159, v189, -v190
	v_exp_f32_e32 v158, v158
	v_fma_f32 v160, v160, v189, -v190
	v_exp_f32_e32 v159, v159
	v_fma_f32 v161, v161, v189, -v190
	v_exp_f32_e32 v160, v160
	v_fma_f32 v162, v162, v189, -v190
	v_exp_f32_e32 v161, v161
	v_fma_f32 v163, v163, v189, -v190
	v_exp_f32_e32 v162, v162
	v_exp_f32_e32 v163, v163
	v_add_f32_e32 v188, v148, v149
	v_add_f32_e32 v189, v150, v151
	v_add_f32_e32 v190, v152, v153
	v_add_f32_e32 v191, v154, v155
	v_add_f32_e32 v192, v156, v157
	v_add_f32_e32 v193, v158, v159
	v_add_f32_e32 v194, v160, v161
	v_add_f32_e32 v195, v162, v163
	v_add_f32_e32 v188, v188, v189
	v_add_f32_e32 v190, v190, v191
	v_add_f32_e32 v192, v192, v193
	v_add_f32_e32 v194, v194, v195
	v_add_f32_e32 v188, v188, v190
	v_add_f32_e32 v192, v192, v194
	v_add_f32_e32 v188, v188, v192
	v_cmp_lt_f32_e32 vcc, s101, v188
	s_cbranch_vccnz .Lv4_rare_h3
.Lv4_cont_h3:
	v_add_f32_e32 v224, v224, v188
	v_cvt_pk_bf16_f32 v155, v154, v155
	v_cvt_pk_bf16_f32 v154, v152, v153
	v_cvt_pk_bf16_f32 v152, v148, v149
	v_cvt_pk_bf16_f32 v153, v150, v151
	v_cvt_pk_bf16_f32 v148, v156, v157
	v_cvt_pk_bf16_f32 v149, v158, v159
	v_cvt_pk_bf16_f32 v150, v160, v161
	v_cvt_pk_bf16_f32 v151, v162, v163
	s_barrier
	s_setprio 0
	s_waitcnt lgkmcnt(2)
	v_mfma_f32_32x32x16_bf16 v[4:19], v[152:155], v[184:187], v[4:19]
	ds_read_b64_tr_b16 v[156:157], v222 offset:33792
	ds_read_b64_tr_b16 v[158:159], v222 offset:37888
	s_waitcnt lgkmcnt(2)
	v_mfma_f32_32x32x16_bf16 v[116:131], v[152:155], v[180:183], v[116:131]
	ds_read_b64_tr_b16 v[160:161], v222 offset:34304
	ds_read_b64_tr_b16 v[162:163], v222 offset:38400
	s_add_i32 m0, s83, 0
	s_nop 0
	global_load_lds_dwordx4 v200, s[86:87]
	s_waitcnt lgkmcnt(2)
	v_mfma_f32_32x32x16_bf16 v[100:115], v[152:155], v[156:159], v[100:115]
	ds_read_b64_tr_b16 v[156:157], v222 offset:34816
	ds_read_b64_tr_b16 v[158:159], v222 offset:38912
	s_waitcnt lgkmcnt(2)
	v_mfma_f32_32x32x16_bf16 v[84:99], v[152:155], v[160:163], v[84:99]
	ds_read_b64_tr_b16 v[160:161], v222 offset:35328
	ds_read_b64_tr_b16 v[162:163], v222 offset:39424
	s_add_i32 m0, s82, 0
	s_nop 0
	global_load_lds_dwordx4 v204, s[2:3]
	s_waitcnt lgkmcnt(2)
	v_mfma_f32_32x32x16_bf16 v[68:83], v[152:155], v[156:159], v[68:83]
	ds_read_b64_tr_b16 v[156:157], v222 offset:35840
	ds_read_b64_tr_b16 v[158:159], v222 offset:39936
	s_waitcnt lgkmcnt(2)
	v_mfma_f32_32x32x16_bf16 v[52:67], v[152:155], v[160:163], v[52:67]
	ds_read_b64_tr_b16 v[160:161], v222 offset:36352
	ds_read_b64_tr_b16 v[162:163], v222 offset:40448
	s_add_u32 s2, s2, 0x80
	s_addc_u32 s3, s3, 0
	s_add_i32 m0, s82, 0x400
	s_nop 0
	global_load_lds_dwordx4 v204, s[2:3]
	s_waitcnt lgkmcnt(2)
	v_mfma_f32_32x32x16_bf16 v[36:51], v[152:155], v[156:159], v[36:51]
	ds_read_b64_tr_b16 v[156:157], v222 offset:40960
	ds_read_b64_tr_b16 v[158:159], v222 offset:45056
	s_waitcnt lgkmcnt(2)
	v_mfma_f32_32x32x16_bf16 v[20:35], v[152:155], v[160:163], v[20:35]
	ds_read_b64_tr_b16 v[152:153], v222 offset:41472
	ds_read_b64_tr_b16 v[154:155], v222 offset:45568
	s_add_u32 s2, s2, 0x80
	s_addc_u32 s3, s3, 0
	s_add_i32 m0, s82, 0x800
	s_nop 0
	global_load_lds_dwordx4 v204, s[2:3]
	s_waitcnt lgkmcnt(2)
	v_mfma_f32_32x32x16_bf16 v[4:19], v[148:151], v[156:159], v[4:19]
	ds_read_b64_tr_b16 v[156:157], v222 offset:41984
	ds_read_b64_tr_b16 v[158:159], v222 offset:46080
	s_waitcnt lgkmcnt(2)
	v_mfma_f32_32x32x16_bf16 v[116:131], v[148:151], v[152:155], v[116:131]
	ds_read_b64_tr_b16 v[152:153], v222 offset:42496
	ds_read_b64_tr_b16 v[154:155], v222 offset:46592
	s_add_u32 s2, s2, 0x80
	s_addc_u32 s3, s3, 0
	s_add_i32 m0, s82, 0xc00
	s_nop 0
	global_load_lds_dwordx4 v204, s[2:3]
	s_waitcnt lgkmcnt(2)
	v_mfma_f32_32x32x16_bf16 v[100:115], v[148:151], v[156:159], v[100:115]
	ds_read_b64_tr_b16 v[156:157], v222 offset:43008
	ds_read_b64_tr_b16 v[158:159], v222 offset:47104
	s_waitcnt lgkmcnt(2)
	v_mfma_f32_32x32x16_bf16 v[84:99], v[148:151], v[152:155], v[84:99]
	ds_read_b64_tr_b16 v[152:153], v222 offset:43520
	ds_read_b64_tr_b16 v[154:155], v222 offset:47616
	s_waitcnt lgkmcnt(2)
	v_mfma_f32_32x32x16_bf16 v[68:83], v[148:151], v[156:159], v[68:83]
	ds_read_b64_tr_b16 v[156:157], v222 offset:44032
	ds_read_b64_tr_b16 v[158:159], v222 offset:48128
	s_waitcnt lgkmcnt(2)
	v_mfma_f32_32x32x16_bf16 v[52:67], v[148:151], v[152:155], v[52:67]
	ds_read_b64_tr_b16 v[152:153], v222 offset:44544
	ds_read_b64_tr_b16 v[154:155], v222 offset:48640
	s_waitcnt lgkmcnt(2)
	v_mfma_f32_32x32x16_bf16 v[36:51], v[148:151], v[156:159], v[36:51]
	s_waitcnt lgkmcnt(0)
	v_mfma_f32_32x32x16_bf16 v[20:35], v[148:151], v[152:155], v[20:35]
	s_barrier
	s_setprio 1
	ds_read_b128 v[180:183], v225 offset:20480
	ds_read_b128 v[184:187], v226 offset:20480
	s_waitcnt lgkmcnt(1)
	v_mfma_i32_32x32x32_i8 v[148:163], v[180:183], v[164:167], v[132:147]
	ds_read_b128 v[180:183], v227 offset:20480
	s_waitcnt lgkmcnt(1)
	v_mfma_i32_32x32x32_i8 v[148:163], v[184:187], v[168:171], v[148:163]
	ds_read_b128 v[188:191], v228 offset:20480
	s_waitcnt lgkmcnt(1)
	v_mfma_i32_32x32x32_i8 v[148:163], v[180:183], v[172:175], v[148:163]
	ds_read_b64_tr_b16 v[184:185], v222 offset:49152
	ds_read_b64_tr_b16 v[186:187], v222 offset:53248
	s_waitcnt lgkmcnt(2)
	v_mfma_i32_32x32x32_i8 v[148:163], v[188:191], v[176:179], v[148:163]
	ds_read_b64_tr_b16 v[180:181], v222 offset:49664
	ds_read_b64_tr_b16 v[182:183], v222 offset:53760
	s_nop 9
	v_mul_f32_e32 v189, v221, v236
	v_fma_f32 v190, s100, v189, v255
	v_fma_f32 v148, v148, v189, -v190
	v_fma_f32 v149, v149, v189, -v190
	v_exp_f32_e32 v148, v148
	v_fma_f32 v150, v150, v189, -v190
	v_exp_f32_e32 v149, v149
	v_fma_f32 v151, v151, v189, -v190
	v_exp_f32_e32 v150, v150
	v_fma_f32 v152, v152, v189, -v190
	v_exp_f32_e32 v151, v151
	v_fma_f32 v153, v153, v189, -v190
	v_exp_f32_e32 v152, v152
	v_fma_f32 v154, v154, v189, -v190
	v_exp_f32_e32 v153, v153
	v_fma_f32 v155, v155, v189, -v190
	v_exp_f32_e32 v154, v154
	v_fma_f32 v156, v156, v189, -v190
	v_exp_f32_e32 v155, v155
	v_fma_f32 v157, v157, v189, -v190
	v_exp_f32_e32 v156, v156
	v_fma_f32 v158, v158, v189, -v190
	v_exp_f32_e32 v157, v157
	v_fma_f32 v159, v159, v189, -v190
	v_exp_f32_e32 v158, v158
	v_fma_f32 v160, v160, v189, -v190
	v_exp_f32_e32 v159, v159
	v_fma_f32 v161, v161, v189, -v190
	v_exp_f32_e32 v160, v160
	v_fma_f32 v162, v162, v189, -v190
	v_exp_f32_e32 v161, v161
	v_fma_f32 v163, v163, v189, -v190
	v_exp_f32_e32 v162, v162
	v_exp_f32_e32 v163, v163
	v_add_f32_e32 v188, v148, v149
	v_add_f32_e32 v189, v150, v151
	v_add_f32_e32 v190, v152, v153
	v_add_f32_e32 v191, v154, v155
	v_add_f32_e32 v192, v156, v157
	v_add_f32_e32 v193, v158, v159
	v_add_f32_e32 v194, v160, v161
	v_add_f32_e32 v195, v162, v163
	v_add_f32_e32 v188, v188, v189
	v_add_f32_e32 v190, v190, v191
	v_add_f32_e32 v192, v192, v193
	v_add_f32_e32 v194, v194, v195
	v_add_f32_e32 v188, v188, v190
	v_add_f32_e32 v192, v192, v194
	v_add_f32_e32 v188, v188, v192
	v_cmp_lt_f32_e32 vcc, s101, v188
	s_cbranch_vccnz .Lv4_rare_h4
.Lv4_cont_h4:
	v_add_f32_e32 v224, v224, v188
	v_cvt_pk_bf16_f32 v155, v154, v155
	v_cvt_pk_bf16_f32 v154, v152, v153
	v_cvt_pk_bf16_f32 v152, v148, v149
	v_cvt_pk_bf16_f32 v153, v150, v151
	v_cvt_pk_bf16_f32 v148, v156, v157
	v_cvt_pk_bf16_f32 v149, v158, v159
	v_cvt_pk_bf16_f32 v150, v160, v161
	v_cvt_pk_bf16_f32 v151, v162, v163
	s_barrier
	s_setprio 0
	s_waitcnt lgkmcnt(2)
	v_mfma_f32_32x32x16_bf16 v[4:19], v[152:155], v[184:187], v[4:19]
	ds_read_b64_tr_b16 v[156:157], v222 offset:50176
	ds_read_b64_tr_b16 v[158:159], v222 offset:54272
	s_waitcnt lgkmcnt(2)
	v_mfma_f32_32x32x16_bf16 v[116:131], v[152:155], v[180:183], v[116:131]
	ds_read_b64_tr_b16 v[160:161], v222 offset:50688
	ds_read_b64_tr_b16 v[162:163], v222 offset:54784
	s_waitcnt lgkmcnt(2)
	v_mfma_f32_32x32x16_bf16 v[100:115], v[152:155], v[156:159], v[100:115]
	ds_read_b64_tr_b16 v[156:157], v222 offset:51200
	ds_read_b64_tr_b16 v[158:159], v222 offset:55296
	s_waitcnt lgkmcnt(2)
	v_mfma_f32_32x32x16_bf16 v[84:99], v[152:155], v[160:163], v[84:99]
	ds_read_b64_tr_b16 v[160:161], v222 offset:51712
	ds_read_b64_tr_b16 v[162:163], v222 offset:55808
	s_waitcnt lgkmcnt(2)
	v_mfma_f32_32x32x16_bf16 v[68:83], v[152:155], v[156:159], v[68:83]
	ds_read_b64_tr_b16 v[156:157], v222 offset:52224
	ds_read_b64_tr_b16 v[158:159], v222 offset:56320
	s_waitcnt lgkmcnt(2)
	v_mfma_f32_32x32x16_bf16 v[52:67], v[152:155], v[160:163], v[52:67]
	ds_read_b64_tr_b16 v[160:161], v222 offset:52736
	ds_read_b64_tr_b16 v[162:163], v222 offset:56832
	s_waitcnt lgkmcnt(2)
	v_mfma_f32_32x32x16_bf16 v[36:51], v[152:155], v[156:159], v[36:51]
	ds_read_b64_tr_b16 v[156:157], v222 offset:57344
	ds_read_b64_tr_b16 v[158:159], v222 offset:61440
	s_waitcnt lgkmcnt(2)
	v_mfma_f32_32x32x16_bf16 v[20:35], v[152:155], v[160:163], v[20:35]
	ds_read_b64_tr_b16 v[152:153], v222 offset:57856
	ds_read_b64_tr_b16 v[154:155], v222 offset:61952
	s_waitcnt lgkmcnt(2)
	v_mfma_f32_32x32x16_bf16 v[4:19], v[148:151], v[156:159], v[4:19]
	ds_read_b64_tr_b16 v[156:157], v222 offset:58368
	ds_read_b64_tr_b16 v[158:159], v222 offset:62464
	s_waitcnt lgkmcnt(2)
	v_mfma_f32_32x32x16_bf16 v[116:131], v[148:151], v[152:155], v[116:131]
	ds_read_b64_tr_b16 v[152:153], v222 offset:58880
	ds_read_b64_tr_b16 v[154:155], v222 offset:62976
	s_waitcnt lgkmcnt(2)
	v_mfma_f32_32x32x16_bf16 v[100:115], v[148:151], v[156:159], v[100:115]
	ds_read_b64_tr_b16 v[156:157], v222 offset:59392
	ds_read_b64_tr_b16 v[158:159], v222 offset:63488
	s_waitcnt lgkmcnt(2)
	v_mfma_f32_32x32x16_bf16 v[84:99], v[148:151], v[152:155], v[84:99]
	ds_read_b64_tr_b16 v[152:153], v222 offset:59904
	ds_read_b64_tr_b16 v[154:155], v222 offset:64000
	s_waitcnt lgkmcnt(2)
	v_mfma_f32_32x32x16_bf16 v[68:83], v[148:151], v[156:159], v[68:83]
	ds_read_b64_tr_b16 v[156:157], v222 offset:60416
	ds_read_b64_tr_b16 v[158:159], v222 offset:64512
	s_waitcnt lgkmcnt(2)
	v_mfma_f32_32x32x16_bf16 v[52:67], v[148:151], v[152:155], v[52:67]
	ds_read_b64_tr_b16 v[152:153], v222 offset:60928
	ds_read_b64_tr_b16 v[154:155], v222 offset:65024
	s_waitcnt lgkmcnt(2)
	v_mfma_f32_32x32x16_bf16 v[36:51], v[148:151], v[156:159], v[36:51]
	s_waitcnt lgkmcnt(0)
	v_mfma_f32_32x32x16_bf16 v[20:35], v[148:151], v[152:155], v[20:35]
	s_add_i32 s2, s79, 2
	s_cmp_ge_u32 s79, s70
	s_cbranch_scc1 .LBB0_557
	s_mov_b32 s79, s2
	s_branch .LBB0_538
.Lv4_rare_h1:
	ds_read_b128 v[244:247], v225
	ds_read_b128 v[248:251], v226
	s_waitcnt lgkmcnt(1)
	v_mfma_i32_32x32x32_i8 v[148:163], v[244:247], v[164:167], v[132:147]
	ds_read_b128 v[244:247], v227
	s_waitcnt lgkmcnt(1)
	v_mfma_i32_32x32x32_i8 v[148:163], v[248:251], v[168:171], v[148:163]
	ds_read_b128 v[248:251], v228
	s_waitcnt lgkmcnt(1)
	v_mfma_i32_32x32x32_i8 v[148:163], v[244:247], v[172:175], v[148:163]
	s_waitcnt lgkmcnt(0)
	v_mfma_i32_32x32x32_i8 v[148:163], v[248:251], v[176:179], v[148:163]
	s_nop 15
	v_max3_f32 v188, v148, v149, v150
	v_max3_f32 v189, v151, v152, v153
	v_max3_f32 v190, v154, v155, v156
	v_max3_f32 v191, v157, v158, v159
	v_max3_f32 v192, v160, v161, v162
	v_max3_f32 v188, v188, v189, v190
	v_max3_f32 v191, v191, v192, v163
	v_max_f32_e32 v188, v188, v191
	v_add_f32_e32 v188, 0xcb400000, v188
	v_mov_b32_e32 v189, v188
	s_nop 1
	v_permlane32_swap_b32_e32 v188, v189
	v_max_f32_e32 v188, v188, v189
	v_mul_f32_e32 v189, v206, v188
	v_fma_f32 v188, v206, v188, -v237
	v_max_f32_e32 v189, v237, v189
	v_cmp_gt_f32_e32 vcc, v188, v220
	s_nop 1
	v_cndmask_b32_e32 v189, v237, v189, vcc
	v_sub_f32_e32 v188, v237, v189
	v_mul_f32_e32 v188, v221, v188
	v_exp_f32_e32 v254, v188
	v_mov_b32_e32 v237, v189
	v_mul_f32_e32 v255, v221, v189
	v_mul_f32_e32 v224, v224, v254
	s_and_saveexec_b64 vcc, s[0:1]
	ds_write_b32 v223, v254
	s_or_b64 exec, exec, vcc
	s_waitcnt lgkmcnt(0)
	v_add_u32_e32 v253, s78, v218
	ds_read_b128 v[244:247], v253 offset:96
	ds_read_b128 v[248:251], v253 offset:64
	s_waitcnt lgkmcnt(1)
	v_pk_mul_f32 v[16:17], v[16:17], v[244:245]
	v_pk_mul_f32 v[18:19], v[18:19], v[246:247]
	v_pk_mul_f32 v[128:129], v[128:129], v[244:245]
	v_pk_mul_f32 v[130:131], v[130:131], v[246:247]
	v_pk_mul_f32 v[112:113], v[112:113], v[244:245]
	v_pk_mul_f32 v[114:115], v[114:115], v[246:247]
	v_pk_mul_f32 v[96:97], v[96:97], v[244:245]
	v_pk_mul_f32 v[98:99], v[98:99], v[246:247]
	v_pk_mul_f32 v[80:81], v[80:81], v[244:245]
	v_pk_mul_f32 v[82:83], v[82:83], v[246:247]
	v_pk_mul_f32 v[64:65], v[64:65], v[244:245]
	v_pk_mul_f32 v[66:67], v[66:67], v[246:247]
	v_pk_mul_f32 v[48:49], v[48:49], v[244:245]
	v_pk_mul_f32 v[50:51], v[50:51], v[246:247]
	v_pk_mul_f32 v[32:33], v[32:33], v[244:245]
	v_pk_mul_f32 v[34:35], v[34:35], v[246:247]
	s_waitcnt lgkmcnt(0)
	v_pk_mul_f32 v[12:13], v[12:13], v[248:249]
	v_pk_mul_f32 v[14:15], v[14:15], v[250:251]
	v_pk_mul_f32 v[124:125], v[124:125], v[248:249]
	v_pk_mul_f32 v[126:127], v[126:127], v[250:251]
	v_pk_mul_f32 v[108:109], v[108:109], v[248:249]
	v_pk_mul_f32 v[110:111], v[110:111], v[250:251]
	v_pk_mul_f32 v[92:93], v[92:93], v[248:249]
	v_pk_mul_f32 v[94:95], v[94:95], v[250:251]
	v_pk_mul_f32 v[76:77], v[76:77], v[248:249]
	v_pk_mul_f32 v[78:79], v[78:79], v[250:251]
	v_pk_mul_f32 v[60:61], v[60:61], v[248:249]
	v_pk_mul_f32 v[62:63], v[62:63], v[250:251]
	v_pk_mul_f32 v[44:45], v[44:45], v[248:249]
	v_pk_mul_f32 v[46:47], v[46:47], v[250:251]
	v_pk_mul_f32 v[28:29], v[28:29], v[248:249]
	v_pk_mul_f32 v[30:31], v[30:31], v[250:251]
	ds_read_b128 v[244:247], v253 offset:32
	ds_read_b128 v[248:251], v253
	s_waitcnt lgkmcnt(1)
	v_pk_mul_f32 v[8:9], v[8:9], v[244:245]
	v_pk_mul_f32 v[10:11], v[10:11], v[246:247]
	v_pk_mul_f32 v[120:121], v[120:121], v[244:245]
	v_pk_mul_f32 v[122:123], v[122:123], v[246:247]
	v_pk_mul_f32 v[104:105], v[104:105], v[244:245]
	v_pk_mul_f32 v[106:107], v[106:107], v[246:247]
	v_pk_mul_f32 v[88:89], v[88:89], v[244:245]
	v_pk_mul_f32 v[90:91], v[90:91], v[246:247]
	v_pk_mul_f32 v[72:73], v[72:73], v[244:245]
	v_pk_mul_f32 v[74:75], v[74:75], v[246:247]
	v_pk_mul_f32 v[56:57], v[56:57], v[244:245]
	v_pk_mul_f32 v[58:59], v[58:59], v[246:247]
	v_pk_mul_f32 v[40:41], v[40:41], v[244:245]
	v_pk_mul_f32 v[42:43], v[42:43], v[246:247]
	v_pk_mul_f32 v[24:25], v[24:25], v[244:245]
	v_pk_mul_f32 v[26:27], v[26:27], v[246:247]
	s_waitcnt lgkmcnt(0)
	v_pk_mul_f32 v[4:5], v[4:5], v[248:249]
	v_pk_mul_f32 v[6:7], v[6:7], v[250:251]
	v_pk_mul_f32 v[116:117], v[116:117], v[248:249]
	v_pk_mul_f32 v[118:119], v[118:119], v[250:251]
	v_pk_mul_f32 v[100:101], v[100:101], v[248:249]
	v_pk_mul_f32 v[102:103], v[102:103], v[250:251]
	v_pk_mul_f32 v[84:85], v[84:85], v[248:249]
	v_pk_mul_f32 v[86:87], v[86:87], v[250:251]
	v_pk_mul_f32 v[68:69], v[68:69], v[248:249]
	v_pk_mul_f32 v[70:71], v[70:71], v[250:251]
	v_pk_mul_f32 v[52:53], v[52:53], v[248:249]
	v_pk_mul_f32 v[54:55], v[54:55], v[250:251]
	v_pk_mul_f32 v[36:37], v[36:37], v[248:249]
	v_pk_mul_f32 v[38:39], v[38:39], v[250:251]
	v_pk_mul_f32 v[20:21], v[20:21], v[248:249]
	v_pk_mul_f32 v[22:23], v[22:23], v[250:251]
	v_mul_f32_e32 v189, v221, v206
	v_fma_f32 v190, s100, v189, v255
	v_fma_f32 v148, v148, v189, -v190
	v_fma_f32 v149, v149, v189, -v190
	v_exp_f32_e32 v148, v148
	v_fma_f32 v150, v150, v189, -v190
	v_exp_f32_e32 v149, v149
	v_fma_f32 v151, v151, v189, -v190
	v_exp_f32_e32 v150, v150
	v_fma_f32 v152, v152, v189, -v190
	v_exp_f32_e32 v151, v151
	v_fma_f32 v153, v153, v189, -v190
	v_exp_f32_e32 v152, v152
	v_fma_f32 v154, v154, v189, -v190
	v_exp_f32_e32 v153, v153
	v_fma_f32 v155, v155, v189, -v190
	v_exp_f32_e32 v154, v154
	v_fma_f32 v156, v156, v189, -v190
	v_exp_f32_e32 v155, v155
	v_fma_f32 v157, v157, v189, -v190
	v_exp_f32_e32 v156, v156
	v_fma_f32 v158, v158, v189, -v190
	v_exp_f32_e32 v157, v157
	v_fma_f32 v159, v159, v189, -v190
	v_exp_f32_e32 v158, v158
	v_fma_f32 v160, v160, v189, -v190
	v_exp_f32_e32 v159, v159
	v_fma_f32 v161, v161, v189, -v190
	v_exp_f32_e32 v160, v160
	v_fma_f32 v162, v162, v189, -v190
	v_exp_f32_e32 v161, v161
	v_fma_f32 v163, v163, v189, -v190
	v_exp_f32_e32 v162, v162
	v_exp_f32_e32 v163, v163
	v_add_f32_e32 v188, v148, v149
	v_add_f32_e32 v189, v150, v151
	v_add_f32_e32 v190, v152, v153
	v_add_f32_e32 v191, v154, v155
	v_add_f32_e32 v192, v156, v157
	v_add_f32_e32 v193, v158, v159
	v_add_f32_e32 v194, v160, v161
	v_add_f32_e32 v195, v162, v163
	v_add_f32_e32 v188, v188, v189
	v_add_f32_e32 v190, v190, v191
	v_add_f32_e32 v192, v192, v193
	v_add_f32_e32 v194, v194, v195
	v_add_f32_e32 v188, v188, v190
	v_add_f32_e32 v192, v192, v194
	v_add_f32_e32 v188, v188, v192
	s_branch .Lv4_cont_h1
.Lv4_rare_h2:
	ds_read_b128 v[244:247], v225 offset:4096
	ds_read_b128 v[248:251], v226 offset:4096
	s_waitcnt lgkmcnt(1)
	v_mfma_i32_32x32x32_i8 v[148:163], v[244:247], v[164:167], v[132:147]
	ds_read_b128 v[244:247], v227 offset:4096
	s_waitcnt lgkmcnt(1)
	v_mfma_i32_32x32x32_i8 v[148:163], v[248:251], v[168:171], v[148:163]
	ds_read_b128 v[248:251], v228 offset:4096
	s_waitcnt lgkmcnt(1)
	v_mfma_i32_32x32x32_i8 v[148:163], v[244:247], v[172:175], v[148:163]
	s_waitcnt lgkmcnt(0)
	v_mfma_i32_32x32x32_i8 v[148:163], v[248:251], v[176:179], v[148:163]
	s_nop 15
	v_max3_f32 v188, v148, v149, v150
	v_max3_f32 v189, v151, v152, v153
	v_max3_f32 v190, v154, v155, v156
	v_max3_f32 v191, v157, v158, v159
	v_max3_f32 v192, v160, v161, v162
	v_max3_f32 v188, v188, v189, v190
	v_max3_f32 v191, v191, v192, v163
	v_max_f32_e32 v188, v188, v191
	v_add_f32_e32 v188, 0xcb400000, v188
	v_mov_b32_e32 v189, v188
	s_nop 1
	v_permlane32_swap_b32_e32 v188, v189
	v_max_f32_e32 v188, v188, v189
	v_mul_f32_e32 v189, v207, v188
	v_fma_f32 v188, v207, v188, -v237
	v_max_f32_e32 v189, v237, v189
	v_cmp_gt_f32_e32 vcc, v188, v220
	s_nop 1
	v_cndmask_b32_e32 v189, v237, v189, vcc
	v_sub_f32_e32 v188, v237, v189
	v_mul_f32_e32 v188, v221, v188
	v_exp_f32_e32 v254, v188
	v_mov_b32_e32 v237, v189
	v_mul_f32_e32 v255, v221, v189
	v_mul_f32_e32 v224, v224, v254
	s_and_saveexec_b64 vcc, s[0:1]
	ds_write_b32 v223, v254
	s_or_b64 exec, exec, vcc
	s_waitcnt lgkmcnt(0)
	v_add_u32_e32 v253, s78, v218
	ds_read_b128 v[244:247], v253 offset:96
	ds_read_b128 v[248:251], v253 offset:64
	s_waitcnt lgkmcnt(1)
	v_pk_mul_f32 v[16:17], v[16:17], v[244:245]
	v_pk_mul_f32 v[18:19], v[18:19], v[246:247]
	v_pk_mul_f32 v[128:129], v[128:129], v[244:245]
	v_pk_mul_f32 v[130:131], v[130:131], v[246:247]
	v_pk_mul_f32 v[112:113], v[112:113], v[244:245]
	v_pk_mul_f32 v[114:115], v[114:115], v[246:247]
	v_pk_mul_f32 v[96:97], v[96:97], v[244:245]
	v_pk_mul_f32 v[98:99], v[98:99], v[246:247]
	v_pk_mul_f32 v[80:81], v[80:81], v[244:245]
	v_pk_mul_f32 v[82:83], v[82:83], v[246:247]
	v_pk_mul_f32 v[64:65], v[64:65], v[244:245]
	v_pk_mul_f32 v[66:67], v[66:67], v[246:247]
	v_pk_mul_f32 v[48:49], v[48:49], v[244:245]
	v_pk_mul_f32 v[50:51], v[50:51], v[246:247]
	v_pk_mul_f32 v[32:33], v[32:33], v[244:245]
	v_pk_mul_f32 v[34:35], v[34:35], v[246:247]
	s_waitcnt lgkmcnt(0)
	v_pk_mul_f32 v[12:13], v[12:13], v[248:249]
	v_pk_mul_f32 v[14:15], v[14:15], v[250:251]
	v_pk_mul_f32 v[124:125], v[124:125], v[248:249]
	v_pk_mul_f32 v[126:127], v[126:127], v[250:251]
	v_pk_mul_f32 v[108:109], v[108:109], v[248:249]
	v_pk_mul_f32 v[110:111], v[110:111], v[250:251]
	v_pk_mul_f32 v[92:93], v[92:93], v[248:249]
	v_pk_mul_f32 v[94:95], v[94:95], v[250:251]
	v_pk_mul_f32 v[76:77], v[76:77], v[248:249]
	v_pk_mul_f32 v[78:79], v[78:79], v[250:251]
	v_pk_mul_f32 v[60:61], v[60:61], v[248:249]
	v_pk_mul_f32 v[62:63], v[62:63], v[250:251]
	v_pk_mul_f32 v[44:45], v[44:45], v[248:249]
	v_pk_mul_f32 v[46:47], v[46:47], v[250:251]
	v_pk_mul_f32 v[28:29], v[28:29], v[248:249]
	v_pk_mul_f32 v[30:31], v[30:31], v[250:251]
	ds_read_b128 v[244:247], v253 offset:32
	ds_read_b128 v[248:251], v253
	s_waitcnt lgkmcnt(1)
	v_pk_mul_f32 v[8:9], v[8:9], v[244:245]
	v_pk_mul_f32 v[10:11], v[10:11], v[246:247]
	v_pk_mul_f32 v[120:121], v[120:121], v[244:245]
	v_pk_mul_f32 v[122:123], v[122:123], v[246:247]
	v_pk_mul_f32 v[104:105], v[104:105], v[244:245]
	v_pk_mul_f32 v[106:107], v[106:107], v[246:247]
	v_pk_mul_f32 v[88:89], v[88:89], v[244:245]
	v_pk_mul_f32 v[90:91], v[90:91], v[246:247]
	v_pk_mul_f32 v[72:73], v[72:73], v[244:245]
	v_pk_mul_f32 v[74:75], v[74:75], v[246:247]
	v_pk_mul_f32 v[56:57], v[56:57], v[244:245]
	v_pk_mul_f32 v[58:59], v[58:59], v[246:247]
	v_pk_mul_f32 v[40:41], v[40:41], v[244:245]
	v_pk_mul_f32 v[42:43], v[42:43], v[246:247]
	v_pk_mul_f32 v[24:25], v[24:25], v[244:245]
	v_pk_mul_f32 v[26:27], v[26:27], v[246:247]
	s_waitcnt lgkmcnt(0)
	v_pk_mul_f32 v[4:5], v[4:5], v[248:249]
	v_pk_mul_f32 v[6:7], v[6:7], v[250:251]
	v_pk_mul_f32 v[116:117], v[116:117], v[248:249]
	v_pk_mul_f32 v[118:119], v[118:119], v[250:251]
	v_pk_mul_f32 v[100:101], v[100:101], v[248:249]
	v_pk_mul_f32 v[102:103], v[102:103], v[250:251]
	v_pk_mul_f32 v[84:85], v[84:85], v[248:249]
	v_pk_mul_f32 v[86:87], v[86:87], v[250:251]
	v_pk_mul_f32 v[68:69], v[68:69], v[248:249]
	v_pk_mul_f32 v[70:71], v[70:71], v[250:251]
	v_pk_mul_f32 v[52:53], v[52:53], v[248:249]
	v_pk_mul_f32 v[54:55], v[54:55], v[250:251]
	v_pk_mul_f32 v[36:37], v[36:37], v[248:249]
	v_pk_mul_f32 v[38:39], v[38:39], v[250:251]
	v_pk_mul_f32 v[20:21], v[20:21], v[248:249]
	v_pk_mul_f32 v[22:23], v[22:23], v[250:251]
	v_mul_f32_e32 v189, v221, v207
	v_fma_f32 v190, s100, v189, v255
	v_fma_f32 v148, v148, v189, -v190
	v_fma_f32 v149, v149, v189, -v190
	v_exp_f32_e32 v148, v148
	v_fma_f32 v150, v150, v189, -v190
	v_exp_f32_e32 v149, v149
	v_fma_f32 v151, v151, v189, -v190
	v_exp_f32_e32 v150, v150
	v_fma_f32 v152, v152, v189, -v190
	v_exp_f32_e32 v151, v151
	v_fma_f32 v153, v153, v189, -v190
	v_exp_f32_e32 v152, v152
	v_fma_f32 v154, v154, v189, -v190
	v_exp_f32_e32 v153, v153
	v_fma_f32 v155, v155, v189, -v190
	v_exp_f32_e32 v154, v154
	v_fma_f32 v156, v156, v189, -v190
	v_exp_f32_e32 v155, v155
	v_fma_f32 v157, v157, v189, -v190
	v_exp_f32_e32 v156, v156
	v_fma_f32 v158, v158, v189, -v190
	v_exp_f32_e32 v157, v157
	v_fma_f32 v159, v159, v189, -v190
	v_exp_f32_e32 v158, v158
	v_fma_f32 v160, v160, v189, -v190
	v_exp_f32_e32 v159, v159
	v_fma_f32 v161, v161, v189, -v190
	v_exp_f32_e32 v160, v160
	v_fma_f32 v162, v162, v189, -v190
	v_exp_f32_e32 v161, v161
	v_fma_f32 v163, v163, v189, -v190
	v_exp_f32_e32 v162, v162
	v_exp_f32_e32 v163, v163
	v_add_f32_e32 v188, v148, v149
	v_add_f32_e32 v189, v150, v151
	v_add_f32_e32 v190, v152, v153
	v_add_f32_e32 v191, v154, v155
	v_add_f32_e32 v192, v156, v157
	v_add_f32_e32 v193, v158, v159
	v_add_f32_e32 v194, v160, v161
	v_add_f32_e32 v195, v162, v163
	v_add_f32_e32 v188, v188, v189
	v_add_f32_e32 v190, v190, v191
	v_add_f32_e32 v192, v192, v193
	v_add_f32_e32 v194, v194, v195
	v_add_f32_e32 v188, v188, v190
	v_add_f32_e32 v192, v192, v194
	v_add_f32_e32 v188, v188, v192
	s_branch .Lv4_cont_h2
.Lv4_rare_h3:
	ds_read_b128 v[244:247], v225 offset:16384
	ds_read_b128 v[248:251], v226 offset:16384
	s_waitcnt lgkmcnt(1)
	v_mfma_i32_32x32x32_i8 v[148:163], v[244:247], v[164:167], v[132:147]
	ds_read_b128 v[244:247], v227 offset:16384
	s_waitcnt lgkmcnt(1)
	v_mfma_i32_32x32x32_i8 v[148:163], v[248:251], v[168:171], v[148:163]
	ds_read_b128 v[248:251], v228 offset:16384
	s_waitcnt lgkmcnt(1)
	v_mfma_i32_32x32x32_i8 v[148:163], v[244:247], v[172:175], v[148:163]
	s_waitcnt lgkmcnt(0)
	v_mfma_i32_32x32x32_i8 v[148:163], v[248:251], v[176:179], v[148:163]
	s_nop 15
	v_max3_f32 v188, v148, v149, v150
	v_max3_f32 v189, v151, v152, v153
	v_max3_f32 v190, v154, v155, v156
	v_max3_f32 v191, v157, v158, v159
	v_max3_f32 v192, v160, v161, v162
	v_max3_f32 v188, v188, v189, v190
	v_max3_f32 v191, v191, v192, v163
	v_max_f32_e32 v188, v188, v191
	v_add_f32_e32 v188, 0xcb400000, v188
	v_mov_b32_e32 v189, v188
	s_nop 1
	v_permlane32_swap_b32_e32 v188, v189
	v_max_f32_e32 v188, v188, v189
	v_mul_f32_e32 v189, v208, v188
	v_fma_f32 v188, v208, v188, -v237
	v_max_f32_e32 v189, v237, v189
	v_cmp_gt_f32_e32 vcc, v188, v220
	s_nop 1
	v_cndmask_b32_e32 v189, v237, v189, vcc
	v_sub_f32_e32 v188, v237, v189
	v_mul_f32_e32 v188, v221, v188
	v_exp_f32_e32 v254, v188
	v_mov_b32_e32 v237, v189
	v_mul_f32_e32 v255, v221, v189
	v_mul_f32_e32 v224, v224, v254
	s_and_saveexec_b64 vcc, s[0:1]
	ds_write_b32 v223, v254
	s_or_b64 exec, exec, vcc
	s_waitcnt lgkmcnt(0)
	v_add_u32_e32 v253, s78, v218
	ds_read_b128 v[244:247], v253 offset:96
	ds_read_b128 v[248:251], v253 offset:64
	s_waitcnt lgkmcnt(1)
	v_pk_mul_f32 v[16:17], v[16:17], v[244:245]
	v_pk_mul_f32 v[18:19], v[18:19], v[246:247]
	v_pk_mul_f32 v[128:129], v[128:129], v[244:245]
	v_pk_mul_f32 v[130:131], v[130:131], v[246:247]
	v_pk_mul_f32 v[112:113], v[112:113], v[244:245]
	v_pk_mul_f32 v[114:115], v[114:115], v[246:247]
	v_pk_mul_f32 v[96:97], v[96:97], v[244:245]
	v_pk_mul_f32 v[98:99], v[98:99], v[246:247]
	v_pk_mul_f32 v[80:81], v[80:81], v[244:245]
	v_pk_mul_f32 v[82:83], v[82:83], v[246:247]
	v_pk_mul_f32 v[64:65], v[64:65], v[244:245]
	v_pk_mul_f32 v[66:67], v[66:67], v[246:247]
	v_pk_mul_f32 v[48:49], v[48:49], v[244:245]
	v_pk_mul_f32 v[50:51], v[50:51], v[246:247]
	v_pk_mul_f32 v[32:33], v[32:33], v[244:245]
	v_pk_mul_f32 v[34:35], v[34:35], v[246:247]
	s_waitcnt lgkmcnt(0)
	v_pk_mul_f32 v[12:13], v[12:13], v[248:249]
	v_pk_mul_f32 v[14:15], v[14:15], v[250:251]
	v_pk_mul_f32 v[124:125], v[124:125], v[248:249]
	v_pk_mul_f32 v[126:127], v[126:127], v[250:251]
	v_pk_mul_f32 v[108:109], v[108:109], v[248:249]
	v_pk_mul_f32 v[110:111], v[110:111], v[250:251]
	v_pk_mul_f32 v[92:93], v[92:93], v[248:249]
	v_pk_mul_f32 v[94:95], v[94:95], v[250:251]
	v_pk_mul_f32 v[76:77], v[76:77], v[248:249]
	v_pk_mul_f32 v[78:79], v[78:79], v[250:251]
	v_pk_mul_f32 v[60:61], v[60:61], v[248:249]
	v_pk_mul_f32 v[62:63], v[62:63], v[250:251]
	v_pk_mul_f32 v[44:45], v[44:45], v[248:249]
	v_pk_mul_f32 v[46:47], v[46:47], v[250:251]
	v_pk_mul_f32 v[28:29], v[28:29], v[248:249]
	v_pk_mul_f32 v[30:31], v[30:31], v[250:251]
	ds_read_b128 v[244:247], v253 offset:32
	ds_read_b128 v[248:251], v253
	s_waitcnt lgkmcnt(1)
	v_pk_mul_f32 v[8:9], v[8:9], v[244:245]
	v_pk_mul_f32 v[10:11], v[10:11], v[246:247]
	v_pk_mul_f32 v[120:121], v[120:121], v[244:245]
	v_pk_mul_f32 v[122:123], v[122:123], v[246:247]
	v_pk_mul_f32 v[104:105], v[104:105], v[244:245]
	v_pk_mul_f32 v[106:107], v[106:107], v[246:247]
	v_pk_mul_f32 v[88:89], v[88:89], v[244:245]
	v_pk_mul_f32 v[90:91], v[90:91], v[246:247]
	v_pk_mul_f32 v[72:73], v[72:73], v[244:245]
	v_pk_mul_f32 v[74:75], v[74:75], v[246:247]
	v_pk_mul_f32 v[56:57], v[56:57], v[244:245]
	v_pk_mul_f32 v[58:59], v[58:59], v[246:247]
	v_pk_mul_f32 v[40:41], v[40:41], v[244:245]
	v_pk_mul_f32 v[42:43], v[42:43], v[246:247]
	v_pk_mul_f32 v[24:25], v[24:25], v[244:245]
	v_pk_mul_f32 v[26:27], v[26:27], v[246:247]
	s_waitcnt lgkmcnt(0)
	v_pk_mul_f32 v[4:5], v[4:5], v[248:249]
	v_pk_mul_f32 v[6:7], v[6:7], v[250:251]
	v_pk_mul_f32 v[116:117], v[116:117], v[248:249]
	v_pk_mul_f32 v[118:119], v[118:119], v[250:251]
	v_pk_mul_f32 v[100:101], v[100:101], v[248:249]
	v_pk_mul_f32 v[102:103], v[102:103], v[250:251]
	v_pk_mul_f32 v[84:85], v[84:85], v[248:249]
	v_pk_mul_f32 v[86:87], v[86:87], v[250:251]
	v_pk_mul_f32 v[68:69], v[68:69], v[248:249]
	v_pk_mul_f32 v[70:71], v[70:71], v[250:251]
	v_pk_mul_f32 v[52:53], v[52:53], v[248:249]
	v_pk_mul_f32 v[54:55], v[54:55], v[250:251]
	v_pk_mul_f32 v[36:37], v[36:37], v[248:249]
	v_pk_mul_f32 v[38:39], v[38:39], v[250:251]
	v_pk_mul_f32 v[20:21], v[20:21], v[248:249]
	v_pk_mul_f32 v[22:23], v[22:23], v[250:251]
	v_mul_f32_e32 v189, v221, v208
	v_fma_f32 v190, s100, v189, v255
	v_fma_f32 v148, v148, v189, -v190
	v_fma_f32 v149, v149, v189, -v190
	v_exp_f32_e32 v148, v148
	v_fma_f32 v150, v150, v189, -v190
	v_exp_f32_e32 v149, v149
	v_fma_f32 v151, v151, v189, -v190
	v_exp_f32_e32 v150, v150
	v_fma_f32 v152, v152, v189, -v190
	v_exp_f32_e32 v151, v151
	v_fma_f32 v153, v153, v189, -v190
	v_exp_f32_e32 v152, v152
	v_fma_f32 v154, v154, v189, -v190
	v_exp_f32_e32 v153, v153
	v_fma_f32 v155, v155, v189, -v190
	v_exp_f32_e32 v154, v154
	v_fma_f32 v156, v156, v189, -v190
	v_exp_f32_e32 v155, v155
	v_fma_f32 v157, v157, v189, -v190
	v_exp_f32_e32 v156, v156
	v_fma_f32 v158, v158, v189, -v190
	v_exp_f32_e32 v157, v157
	v_fma_f32 v159, v159, v189, -v190
	v_exp_f32_e32 v158, v158
	v_fma_f32 v160, v160, v189, -v190
	v_exp_f32_e32 v159, v159
	v_fma_f32 v161, v161, v189, -v190
	v_exp_f32_e32 v160, v160
	v_fma_f32 v162, v162, v189, -v190
	v_exp_f32_e32 v161, v161
	v_fma_f32 v163, v163, v189, -v190
	v_exp_f32_e32 v162, v162
	v_exp_f32_e32 v163, v163
	v_add_f32_e32 v188, v148, v149
	v_add_f32_e32 v189, v150, v151
	v_add_f32_e32 v190, v152, v153
	v_add_f32_e32 v191, v154, v155
	v_add_f32_e32 v192, v156, v157
	v_add_f32_e32 v193, v158, v159
	v_add_f32_e32 v194, v160, v161
	v_add_f32_e32 v195, v162, v163
	v_add_f32_e32 v188, v188, v189
	v_add_f32_e32 v190, v190, v191
	v_add_f32_e32 v192, v192, v193
	v_add_f32_e32 v194, v194, v195
	v_add_f32_e32 v188, v188, v190
	v_add_f32_e32 v192, v192, v194
	v_add_f32_e32 v188, v188, v192
	s_branch .Lv4_cont_h3
.Lv4_rare_h4:
	ds_read_b128 v[244:247], v225 offset:20480
	ds_read_b128 v[248:251], v226 offset:20480
	s_waitcnt lgkmcnt(1)
	v_mfma_i32_32x32x32_i8 v[148:163], v[244:247], v[164:167], v[132:147]
	ds_read_b128 v[244:247], v227 offset:20480
	s_waitcnt lgkmcnt(1)
	v_mfma_i32_32x32x32_i8 v[148:163], v[248:251], v[168:171], v[148:163]
	ds_read_b128 v[248:251], v228 offset:20480
	s_waitcnt lgkmcnt(1)
	v_mfma_i32_32x32x32_i8 v[148:163], v[244:247], v[172:175], v[148:163]
	s_waitcnt lgkmcnt(0)
	v_mfma_i32_32x32x32_i8 v[148:163], v[248:251], v[176:179], v[148:163]
	s_nop 15
	v_max3_f32 v188, v148, v149, v150
	v_max3_f32 v189, v151, v152, v153
	v_max3_f32 v190, v154, v155, v156
	v_max3_f32 v191, v157, v158, v159
	v_max3_f32 v192, v160, v161, v162
	v_max3_f32 v188, v188, v189, v190
	v_max3_f32 v191, v191, v192, v163
	v_max_f32_e32 v188, v188, v191
	v_add_f32_e32 v188, 0xcb400000, v188
	v_mov_b32_e32 v189, v188
	s_nop 1
	v_permlane32_swap_b32_e32 v188, v189
	v_max_f32_e32 v188, v188, v189
	v_mul_f32_e32 v189, v236, v188
	v_fma_f32 v188, v236, v188, -v237
	v_max_f32_e32 v189, v237, v189
	v_cmp_gt_f32_e32 vcc, v188, v220
	s_nop 1
	v_cndmask_b32_e32 v189, v237, v189, vcc
	v_sub_f32_e32 v188, v237, v189
	v_mul_f32_e32 v188, v221, v188
	v_exp_f32_e32 v254, v188
	v_mov_b32_e32 v237, v189
	v_mul_f32_e32 v255, v221, v189
	v_mul_f32_e32 v224, v224, v254
	s_and_saveexec_b64 vcc, s[0:1]
	ds_write_b32 v223, v254
	s_or_b64 exec, exec, vcc
	s_waitcnt lgkmcnt(0)
	v_add_u32_e32 v253, s78, v218
	ds_read_b128 v[244:247], v253 offset:96
	ds_read_b128 v[248:251], v253 offset:64
	s_waitcnt lgkmcnt(1)
	v_pk_mul_f32 v[16:17], v[16:17], v[244:245]
	v_pk_mul_f32 v[18:19], v[18:19], v[246:247]
	v_pk_mul_f32 v[128:129], v[128:129], v[244:245]
	v_pk_mul_f32 v[130:131], v[130:131], v[246:247]
	v_pk_mul_f32 v[112:113], v[112:113], v[244:245]
	v_pk_mul_f32 v[114:115], v[114:115], v[246:247]
	v_pk_mul_f32 v[96:97], v[96:97], v[244:245]
	v_pk_mul_f32 v[98:99], v[98:99], v[246:247]
	v_pk_mul_f32 v[80:81], v[80:81], v[244:245]
	v_pk_mul_f32 v[82:83], v[82:83], v[246:247]
	v_pk_mul_f32 v[64:65], v[64:65], v[244:245]
	v_pk_mul_f32 v[66:67], v[66:67], v[246:247]
	v_pk_mul_f32 v[48:49], v[48:49], v[244:245]
	v_pk_mul_f32 v[50:51], v[50:51], v[246:247]
	v_pk_mul_f32 v[32:33], v[32:33], v[244:245]
	v_pk_mul_f32 v[34:35], v[34:35], v[246:247]
	s_waitcnt lgkmcnt(0)
	v_pk_mul_f32 v[12:13], v[12:13], v[248:249]
	v_pk_mul_f32 v[14:15], v[14:15], v[250:251]
	v_pk_mul_f32 v[124:125], v[124:125], v[248:249]
	v_pk_mul_f32 v[126:127], v[126:127], v[250:251]
	v_pk_mul_f32 v[108:109], v[108:109], v[248:249]
	v_pk_mul_f32 v[110:111], v[110:111], v[250:251]
	v_pk_mul_f32 v[92:93], v[92:93], v[248:249]
	v_pk_mul_f32 v[94:95], v[94:95], v[250:251]
	v_pk_mul_f32 v[76:77], v[76:77], v[248:249]
	v_pk_mul_f32 v[78:79], v[78:79], v[250:251]
	v_pk_mul_f32 v[60:61], v[60:61], v[248:249]
	v_pk_mul_f32 v[62:63], v[62:63], v[250:251]
	v_pk_mul_f32 v[44:45], v[44:45], v[248:249]
	v_pk_mul_f32 v[46:47], v[46:47], v[250:251]
	v_pk_mul_f32 v[28:29], v[28:29], v[248:249]
	v_pk_mul_f32 v[30:31], v[30:31], v[250:251]
	ds_read_b128 v[244:247], v253 offset:32
	ds_read_b128 v[248:251], v253
	s_waitcnt lgkmcnt(1)
	v_pk_mul_f32 v[8:9], v[8:9], v[244:245]
	v_pk_mul_f32 v[10:11], v[10:11], v[246:247]
	v_pk_mul_f32 v[120:121], v[120:121], v[244:245]
	v_pk_mul_f32 v[122:123], v[122:123], v[246:247]
	v_pk_mul_f32 v[104:105], v[104:105], v[244:245]
	v_pk_mul_f32 v[106:107], v[106:107], v[246:247]
	v_pk_mul_f32 v[88:89], v[88:89], v[244:245]
	v_pk_mul_f32 v[90:91], v[90:91], v[246:247]
	v_pk_mul_f32 v[72:73], v[72:73], v[244:245]
	v_pk_mul_f32 v[74:75], v[74:75], v[246:247]
	v_pk_mul_f32 v[56:57], v[56:57], v[244:245]
	v_pk_mul_f32 v[58:59], v[58:59], v[246:247]
	v_pk_mul_f32 v[40:41], v[40:41], v[244:245]
	v_pk_mul_f32 v[42:43], v[42:43], v[246:247]
	v_pk_mul_f32 v[24:25], v[24:25], v[244:245]
	v_pk_mul_f32 v[26:27], v[26:27], v[246:247]
	s_waitcnt lgkmcnt(0)
	v_pk_mul_f32 v[4:5], v[4:5], v[248:249]
	v_pk_mul_f32 v[6:7], v[6:7], v[250:251]
	v_pk_mul_f32 v[116:117], v[116:117], v[248:249]
	v_pk_mul_f32 v[118:119], v[118:119], v[250:251]
	v_pk_mul_f32 v[100:101], v[100:101], v[248:249]
	v_pk_mul_f32 v[102:103], v[102:103], v[250:251]
	v_pk_mul_f32 v[84:85], v[84:85], v[248:249]
	v_pk_mul_f32 v[86:87], v[86:87], v[250:251]
	v_pk_mul_f32 v[68:69], v[68:69], v[248:249]
	v_pk_mul_f32 v[70:71], v[70:71], v[250:251]
	v_pk_mul_f32 v[52:53], v[52:53], v[248:249]
	v_pk_mul_f32 v[54:55], v[54:55], v[250:251]
	v_pk_mul_f32 v[36:37], v[36:37], v[248:249]
	v_pk_mul_f32 v[38:39], v[38:39], v[250:251]
	v_pk_mul_f32 v[20:21], v[20:21], v[248:249]
	v_pk_mul_f32 v[22:23], v[22:23], v[250:251]
	v_mul_f32_e32 v189, v221, v236
	v_fma_f32 v190, s100, v189, v255
	v_fma_f32 v148, v148, v189, -v190
	v_fma_f32 v149, v149, v189, -v190
	v_exp_f32_e32 v148, v148
	v_fma_f32 v150, v150, v189, -v190
	v_exp_f32_e32 v149, v149
	v_fma_f32 v151, v151, v189, -v190
	v_exp_f32_e32 v150, v150
	v_fma_f32 v152, v152, v189, -v190
	v_exp_f32_e32 v151, v151
	v_fma_f32 v153, v153, v189, -v190
	v_exp_f32_e32 v152, v152
	v_fma_f32 v154, v154, v189, -v190
	v_exp_f32_e32 v153, v153
	v_fma_f32 v155, v155, v189, -v190
	v_exp_f32_e32 v154, v154
	v_fma_f32 v156, v156, v189, -v190
	v_exp_f32_e32 v155, v155
	v_fma_f32 v157, v157, v189, -v190
	v_exp_f32_e32 v156, v156
	v_fma_f32 v158, v158, v189, -v190
	v_exp_f32_e32 v157, v157
	v_fma_f32 v159, v159, v189, -v190
	v_exp_f32_e32 v158, v158
	v_fma_f32 v160, v160, v189, -v190
	v_exp_f32_e32 v159, v159
	v_fma_f32 v161, v161, v189, -v190
	v_exp_f32_e32 v160, v160
	v_fma_f32 v162, v162, v189, -v190
	v_exp_f32_e32 v161, v161
	v_fma_f32 v163, v163, v189, -v190
	v_exp_f32_e32 v162, v162
	v_exp_f32_e32 v163, v163
	v_add_f32_e32 v188, v148, v149
	v_add_f32_e32 v189, v150, v151
	v_add_f32_e32 v190, v152, v153
	v_add_f32_e32 v191, v154, v155
	v_add_f32_e32 v192, v156, v157
	v_add_f32_e32 v193, v158, v159
	v_add_f32_e32 v194, v160, v161
	v_add_f32_e32 v195, v162, v163
	v_add_f32_e32 v188, v188, v189
	v_add_f32_e32 v190, v190, v191
	v_add_f32_e32 v192, v192, v193
	v_add_f32_e32 v194, v194, v195
	v_add_f32_e32 v188, v188, v190
	v_add_f32_e32 v192, v192, v194
	v_add_f32_e32 v188, v188, v192
	s_branch .Lv4_cont_h4

.Lb4_mid:
	s_barrier
	s_setprio 1
	s_waitcnt vmcnt(0)
	global_load_dwordx2 v[208:209], v201, s[2:3]
	s_cselect_b32 s85, s21, s77
	s_cselect_b32 s88, s20, s76
	s_lshl_b64 s[2:3], s[4:5], 9
	s_add_u32 s2, s88, s2
	ds_read_b128 v[180:183], v225
	ds_read_b128 v[184:187], v226
	s_addc_u32 s3, s85, s3
	s_cmp_lg_u32 0, -1
	s_cselect_b32 s4, 0, 0
	s_add_i32 s85, s4, s80
	s_add_i32 s4, s4, s81
	s_addk_i32 s85, 0x4000
	s_add_i32 s88, s4, 0x10000
	s_waitcnt lgkmcnt(1)
	v_mfma_i32_32x32x32_i8 v[148:163], v[180:183], v[164:167], v[132:147]
	ds_read_b128 v[180:183], v227
	s_waitcnt lgkmcnt(1)
	v_mfma_i32_32x32x32_i8 v[148:163], v[184:187], v[168:171], v[148:163]
	ds_read_b128 v[188:191], v228
	s_waitcnt lgkmcnt(1)
	v_mfma_i32_32x32x32_i8 v[148:163], v[180:183], v[172:175], v[148:163]
	ds_read_b64_tr_b16 v[184:185], v3 offset:32768
	ds_read_b64_tr_b16 v[186:187], v3 offset:36864
	s_waitcnt lgkmcnt(2)
	v_mfma_i32_32x32x32_i8 v[148:163], v[188:191], v[176:179], v[148:163]
	ds_read_b64_tr_b16 v[180:181], v3 offset:33280
	ds_read_b64_tr_b16 v[182:183], v3 offset:37376
	s_nop 9
	v_mul_f32_e32 v189, v221, v206
	v_fma_f32 v190, s100, v189, v255
	v_fma_f32 v148, v148, v189, -v190
	v_fma_f32 v149, v149, v189, -v190
	v_exp_f32_e32 v148, v148
	v_fma_f32 v150, v150, v189, -v190
	v_exp_f32_e32 v149, v149
	v_fma_f32 v151, v151, v189, -v190
	v_exp_f32_e32 v150, v150
	v_fma_f32 v152, v152, v189, -v190
	v_exp_f32_e32 v151, v151
	v_fma_f32 v153, v153, v189, -v190
	v_exp_f32_e32 v152, v152
	v_fma_f32 v154, v154, v189, -v190
	v_exp_f32_e32 v153, v153
	v_fma_f32 v155, v155, v189, -v190
	v_exp_f32_e32 v154, v154
	v_fma_f32 v156, v156, v189, -v190
	v_exp_f32_e32 v155, v155
	v_fma_f32 v157, v157, v189, -v190
	v_exp_f32_e32 v156, v156
	v_fma_f32 v158, v158, v189, -v190
	v_exp_f32_e32 v157, v157
	v_fma_f32 v159, v159, v189, -v190
	v_exp_f32_e32 v158, v158
	v_fma_f32 v160, v160, v189, -v190
	v_exp_f32_e32 v159, v159
	v_fma_f32 v161, v161, v189, -v190
	v_exp_f32_e32 v160, v160
	v_fma_f32 v162, v162, v189, -v190
	v_exp_f32_e32 v161, v161
	v_fma_f32 v163, v163, v189, -v190
	v_exp_f32_e32 v162, v162
	v_exp_f32_e32 v163, v163
	v_add_f32_e32 v188, v148, v149
	v_add_f32_e32 v189, v150, v151
	v_add_f32_e32 v190, v152, v153
	v_add_f32_e32 v191, v154, v155
	v_add_f32_e32 v192, v156, v157
	v_add_f32_e32 v193, v158, v159
	v_add_f32_e32 v194, v160, v161
	v_add_f32_e32 v195, v162, v163
	v_add_f32_e32 v188, v188, v189
	v_add_f32_e32 v190, v190, v191
	v_add_f32_e32 v192, v192, v193
	v_add_f32_e32 v194, v194, v195
	v_add_f32_e32 v188, v188, v190
	v_add_f32_e32 v192, v192, v194
	v_add_f32_e32 v188, v188, v192
	v_cmp_lt_f32_e32 vcc, s101, v188
	s_cbranch_vccnz .Lb5_rare_h1

.Lb5_cont_h2:
	v_add_f32_e32 v224, v224, v188
	v_cvt_pk_bf16_f32 v155, v154, v155
	v_cvt_pk_bf16_f32 v154, v152, v153
	v_cvt_pk_bf16_f32 v152, v148, v149
	v_cvt_pk_bf16_f32 v153, v150, v151
	v_cvt_pk_bf16_f32 v148, v156, v157
	v_cvt_pk_bf16_f32 v149, v158, v159
	v_cvt_pk_bf16_f32 v150, v160, v161
	v_cvt_pk_bf16_f32 v151, v162, v163
	s_min_u32 s85, s79, s84
	s_lshl_b32 s4, s85, 6
	s_cmp_lt_u32 s85, 4
	s_cselect_b64 s[2:3], -1, 0
	s_add_i32 s88, s4, 0xffffff00
	s_and_b64 s[86:87], s[2:3], exec
	s_cselect_b32 s4, s4, s88
	s_cselect_b32 s88, s17, s73
	s_cselect_b32 s89, s16, s72
	s_lshl_b64 s[86:87], s[4:5], 7
	s_add_u32 s86, s89, s86
	s_addc_u32 s87, s88, s87
	s_lshl_b32 s88, s85, 1
	s_mov_b32 s89, s5
	s_lshl_b64 s[88:89], s[88:89], 2
	s_add_u32 s85, s18, s88
	s_addc_u32 s90, s19, s89
	s_add_u32 s88, s74, s88
	s_addc_u32 s89, s75, s89
	s_add_u32 s88, s88, 0xffffffe0
	s_addc_u32 s89, s89, -1
	s_and_b64 s[2:3], s[2:3], exec
	s_waitcnt vmcnt(0)
	v_mov_b32_e32 v236, v209
	s_cselect_b32 s3, s90, s89
	s_cselect_b32 s2, s85, s88
	s_waitcnt vmcnt(0) lgkmcnt(0)
	s_barrier
	s_setprio 0
	s_waitcnt lgkmcnt(2)
	v_mfma_f32_32x32x16_bf16 v[4:19], v[152:155], v[184:187], v[4:19]
	ds_read_b64_tr_b16 v[156:157], v3 offset:50176
	ds_read_b64_tr_b16 v[158:159], v3 offset:54272
	s_waitcnt lgkmcnt(2)
	v_mfma_f32_32x32x16_bf16 v[116:131], v[152:155], v[180:183], v[116:131]
	ds_read_b64_tr_b16 v[160:161], v3 offset:50688
	ds_read_b64_tr_b16 v[162:163], v3 offset:54784
	s_waitcnt lgkmcnt(2)
	v_mfma_f32_32x32x16_bf16 v[100:115], v[152:155], v[156:159], v[100:115]
	ds_read_b64_tr_b16 v[156:157], v3 offset:51200
	ds_read_b64_tr_b16 v[158:159], v3 offset:55296
	s_waitcnt lgkmcnt(2)
	v_mfma_f32_32x32x16_bf16 v[84:99], v[152:155], v[160:163], v[84:99]
	ds_read_b64_tr_b16 v[160:161], v3 offset:51712
	ds_read_b64_tr_b16 v[162:163], v3 offset:55808
	s_waitcnt lgkmcnt(2)
	v_mfma_f32_32x32x16_bf16 v[68:83], v[152:155], v[156:159], v[68:83]
	ds_read_b64_tr_b16 v[156:157], v3 offset:52224
	ds_read_b64_tr_b16 v[158:159], v3 offset:56320
	s_waitcnt lgkmcnt(2)
	v_mfma_f32_32x32x16_bf16 v[52:67], v[152:155], v[160:163], v[52:67]
	ds_read_b64_tr_b16 v[160:161], v3 offset:52736
	ds_read_b64_tr_b16 v[162:163], v3 offset:56832
	s_waitcnt lgkmcnt(2)
	v_mfma_f32_32x32x16_bf16 v[36:51], v[152:155], v[156:159], v[36:51]
	ds_read_b64_tr_b16 v[156:157], v3 offset:57344
	ds_read_b64_tr_b16 v[158:159], v3 offset:61440
	s_waitcnt lgkmcnt(2)
	v_mfma_f32_32x32x16_bf16 v[20:35], v[152:155], v[160:163], v[20:35]
	ds_read_b64_tr_b16 v[152:153], v3 offset:57856
	ds_read_b64_tr_b16 v[154:155], v3 offset:61952
	s_waitcnt lgkmcnt(2)
	v_mfma_f32_32x32x16_bf16 v[4:19], v[148:151], v[156:159], v[4:19]
	ds_read_b64_tr_b16 v[156:157], v3 offset:58368
	ds_read_b64_tr_b16 v[158:159], v3 offset:62464
	s_waitcnt lgkmcnt(2)
	v_mfma_f32_32x32x16_bf16 v[116:131], v[148:151], v[152:155], v[116:131]
	ds_read_b64_tr_b16 v[152:153], v3 offset:58880
	ds_read_b64_tr_b16 v[154:155], v3 offset:62976
	s_waitcnt lgkmcnt(2)
	v_mfma_f32_32x32x16_bf16 v[100:115], v[148:151], v[156:159], v[100:115]
	ds_read_b64_tr_b16 v[156:157], v3 offset:59392
	ds_read_b64_tr_b16 v[158:159], v3 offset:63488
	s_waitcnt lgkmcnt(2)
	v_mfma_f32_32x32x16_bf16 v[84:99], v[148:151], v[152:155], v[84:99]
	ds_read_b64_tr_b16 v[152:153], v3 offset:59904
	ds_read_b64_tr_b16 v[154:155], v3 offset:64000
	s_waitcnt lgkmcnt(2)
	v_mfma_f32_32x32x16_bf16 v[68:83], v[148:151], v[156:159], v[68:83]
	ds_read_b64_tr_b16 v[156:157], v3 offset:60416
	ds_read_b64_tr_b16 v[158:159], v3 offset:64512
	s_waitcnt lgkmcnt(2)
	v_mfma_f32_32x32x16_bf16 v[52:67], v[148:151], v[152:155], v[52:67]
	ds_read_b64_tr_b16 v[152:153], v3 offset:60928
	ds_read_b64_tr_b16 v[154:155], v3 offset:65024
	s_waitcnt lgkmcnt(2)
	v_mfma_f32_32x32x16_bf16 v[36:51], v[148:151], v[156:159], v[36:51]
	s_waitcnt lgkmcnt(0)
	v_mfma_f32_32x32x16_bf16 v[20:35], v[148:151], v[152:155], v[20:35]
	s_barrier
	s_setprio 1
	global_load_dwordx2 v[206:207], v201, s[2:3]
	ds_read_b128 v[180:183], v225 offset:16384
	ds_read_b128 v[184:187], v226 offset:16384
	s_cselect_b32 s85, s21, s77
	s_cselect_b32 s88, s20, s76
	s_lshl_b64 s[2:3], s[4:5], 9
	s_add_u32 s2, s88, s2
	s_addc_u32 s3, s85, s3
	s_waitcnt lgkmcnt(1)
	v_mfma_i32_32x32x32_i8 v[148:163], v[180:183], v[164:167], v[132:147]
	ds_read_b128 v[180:183], v227 offset:16384
	s_waitcnt lgkmcnt(1)
	v_mfma_i32_32x32x32_i8 v[148:163], v[184:187], v[168:171], v[148:163]
	ds_read_b128 v[188:191], v228 offset:16384
	s_waitcnt lgkmcnt(1)
	v_mfma_i32_32x32x32_i8 v[148:163], v[180:183], v[172:175], v[148:163]
	ds_read_b64_tr_b16 v[184:185], v222 offset:32768
	ds_read_b64_tr_b16 v[186:187], v222 offset:36864
	s_waitcnt lgkmcnt(2)
	v_mfma_i32_32x32x32_i8 v[148:163], v[188:191], v[176:179], v[148:163]
	ds_read_b64_tr_b16 v[180:181], v222 offset:33280
	ds_read_b64_tr_b16 v[182:183], v222 offset:37376
	s_nop 9
	s_mov_b32 s90, s94
	v_mul_f32_e32 v189, v221, v208
	v_fma_f32 v190, s100, v189, v255
	v_fma_f32 v148, v148, v189, -v190
	v_fma_f32 v149, v149, v189, -v190
	v_exp_f32_e32 v148, v148
	v_fma_f32 v150, v150, v189, -v190
	v_exp_f32_e32 v149, v149
	v_fma_f32 v151, v151, v189, -v190
	v_exp_f32_e32 v150, v150
	v_fma_f32 v152, v152, v189, -v190
	v_exp_f32_e32 v151, v151
	v_fma_f32 v153, v153, v189, -v190
	v_exp_f32_e32 v152, v152
	v_fma_f32 v154, v154, v189, -v190
	v_exp_f32_e32 v153, v153
	v_fma_f32 v155, v155, v189, -v190
	v_exp_f32_e32 v154, v154
	v_fma_f32 v156, v156, v189, -v190
	v_exp_f32_e32 v155, v155
	v_fma_f32 v157, v157, v189, -v190
	v_exp_f32_e32 v156, v156
	v_fma_f32 v158, v158, v189, -v190
	v_exp_f32_e32 v157, v157
	v_fma_f32 v159, v159, v189, -v190
	v_exp_f32_e32 v158, v158
	v_fma_f32 v160, v160, v189, -v190
	v_exp_f32_e32 v159, v159
	v_fma_f32 v161, v161, v189, -v190
	v_exp_f32_e32 v160, v160
	v_fma_f32 v162, v162, v189, -v190
	v_exp_f32_e32 v161, v161
	v_fma_f32 v163, v163, v189, -v190
	v_exp_f32_e32 v162, v162
	v_exp_f32_e32 v163, v163
	v_add_f32_e32 v188, v148, v149
	v_add_f32_e32 v189, v150, v151
	v_add_f32_e32 v190, v152, v153
	v_add_f32_e32 v191, v154, v155
	v_add_f32_e32 v192, v156, v157
	v_add_f32_e32 v193, v158, v159
	v_add_f32_e32 v194, v160, v161
	v_add_f32_e32 v195, v162, v163
	v_add_f32_e32 v188, v188, v189
	v_add_f32_e32 v190, v190, v191
	v_add_f32_e32 v192, v192, v193
	v_add_f32_e32 v194, v194, v195
	v_add_f32_e32 v188, v188, v190
	v_add_f32_e32 v192, v192, v194
	v_add_f32_e32 v188, v188, v192
	v_cmp_lt_f32_e32 vcc, s101, v188
	s_cbranch_vccnz .Lb5_rare_h3

; __device__ __forceinline__ void attn_unit256q(const bf16* __restrict__ Qb, const unsigned char* __restrict__ Kc, const unsigned char* __restrict__ Kl, const float* __restrict__ Sc, const float* __restrict__ Sl, ...
;     ...
;   for (int j = 0; j < NT; j += 2) {
;     A5_TILE(0, 0, KBUF, VBUF, j);
;     A5_TILE(KBUF, VBUF, 0, 0, j + 1);
;   }
.Lb5_cont_h4:
	v_add_f32_e32 v224, v224, v188
	v_cvt_pk_bf16_f32 v155, v154, v155
	v_cvt_pk_bf16_f32 v154, v152, v153
	v_cvt_pk_bf16_f32 v152, v148, v149
	v_cvt_pk_bf16_f32 v153, v150, v151
	v_cvt_pk_bf16_f32 v148, v156, v157
	v_cvt_pk_bf16_f32 v149, v158, v159
	v_cvt_pk_bf16_f32 v150, v160, v161
	v_cvt_pk_bf16_f32 v151, v162, v163
	s_add_i32 s2, s79, 2
	s_cmp_ge_u32 s79, s70
	s_cbranch_scc1 .Lb4_exit
	s_mov_b32 s79, s2
	s_branch .Lb4_loop
